# baseline (speedup 1.0000x reference)
.Lbar_c0:
	s_barrier
.LBB0_395:
.Lfz1_c0:
	s_and_b32 s27, s86, 0xc000
	v_add_u32_e32 v241, s27, v233
	ds_read_b128 v[144:147], v241 offset:0
	v_xor_b32_e32 v240, 32, v241
	ds_read_b128 v[148:151], v240 offset:0
	v_xor_b32_e32 v239, 64, v241
	ds_read_b128 v[152:155], v239 offset:0
	v_xor_b32_e32 v0, 0x60, v241
	ds_read_b128 v[156:159], v0 offset:0
	s_waitcnt lgkmcnt(0)
	v_mfma_f32_32x32x16_bf16 v[212:227], v[144:147], v[176:179], 0
	v_mfma_f32_32x32x16_bf16 v[212:227], v[148:151], v[180:183], v[212:227]
	v_mfma_f32_32x32x16_bf16 v[212:227], v[152:155], v[184:187], v[212:227]
	v_mfma_f32_32x32x16_bf16 v[212:227], v[156:159], v[188:191], v[212:227]
	ds_read_b128 v[144:147], v241 offset:0x80
	ds_read_b128 v[148:151], v240 offset:0x80
	ds_read_b128 v[152:155], v239 offset:0x80
	ds_read_b128 v[156:159], v0 offset:0x80
	v_cmp_eq_f32_e32 vcc, 0, v238
	v_cmp_eq_f32_e64 s[10:11], 0, v237
	s_and_b64 s[0:1], vcc, s[10:11]
	s_cmp_eq_u64 s[0:1], exec
	s_waitcnt lgkmcnt(0)
	v_mfma_f32_32x32x16_bf16 v[160:175], v[144:147], v[192:195], 0
	v_mfma_f32_32x32x16_bf16 v[160:175], v[148:151], v[196:199], v[160:175]
	v_mfma_f32_32x32x16_bf16 v[160:175], v[152:155], v[200:203], v[160:175]
	v_mfma_f32_32x32x16_bf16 v[160:175], v[156:159], v[204:207], v[160:175]
	s_cbranch_scc0 .LBB0_397
	v_exp_f32_e32 v144, v212
	v_exp_f32_e32 v145, v213
	v_exp_f32_e32 v146, v214
	v_exp_f32_e32 v147, v215
	v_exp_f32_e32 v148, v216
	v_exp_f32_e32 v149, v217
	v_exp_f32_e32 v150, v218
	v_exp_f32_e32 v151, v219
	v_exp_f32_e32 v152, v220
	v_exp_f32_e32 v153, v221
	v_exp_f32_e32 v154, v222
	v_exp_f32_e32 v155, v223
	v_exp_f32_e32 v156, v224
	v_exp_f32_e32 v157, v225
	v_exp_f32_e32 v158, v226
	v_exp_f32_e32 v159, v227
	v_add_f32_e32 v252, v144, v145
	v_add_f32_e32 v253, v146, v147
	v_add_f32_e32 v254, v148, v149
	v_add_f32_e32 v255, v150, v151
	v_add_f32_e32 v252, v252, v152
	v_add_f32_e32 v253, v253, v153
	v_add_f32_e32 v254, v254, v154
	v_add_f32_e32 v255, v255, v155
	v_add_f32_e32 v252, v252, v156
	v_add_f32_e32 v253, v253, v157
	v_add_f32_e32 v254, v254, v158
	v_add_f32_e32 v255, v255, v159
	v_cvt_pk_bf16_f32 v216, v144, v145
	v_cvt_pk_bf16_f32 v217, v146, v147
	v_add_f32_e32 v252, v252, v253
	v_add_f32_e32 v254, v254, v255
	v_cvt_pk_bf16_f32 v218, v148, v149
	v_cvt_pk_bf16_f32 v219, v150, v151
	v_cvt_pk_bf16_f32 v224, v152, v153
	v_add_f32_e32 v252, v252, v254
	v_cvt_pk_bf16_f32 v225, v154, v155
	v_cvt_pk_bf16_f32 v226, v156, v157
	v_cvt_pk_bf16_f32 v227, v158, v159
	v_add_u32_e32 v253, 0xde801b54, v252
	v_cmp_gt_u32_e32 vcc, 0x3bff7543, v253
	s_cmp_lg_u64 vcc, exec
	s_cbranch_scc1 .LBB0_432
	v_add_f32_e32 v15, v15, v252
	v_exp_f32_e32 v144, v160
	v_exp_f32_e32 v145, v161
	v_exp_f32_e32 v146, v162
	v_exp_f32_e32 v147, v163
	v_exp_f32_e32 v148, v164
	v_exp_f32_e32 v149, v165
	v_exp_f32_e32 v150, v166
	v_exp_f32_e32 v151, v167
	v_exp_f32_e32 v152, v168
	v_exp_f32_e32 v153, v169
	v_exp_f32_e32 v154, v170
	v_exp_f32_e32 v155, v171
	v_exp_f32_e32 v156, v172
	v_exp_f32_e32 v157, v173
	v_exp_f32_e32 v158, v174
	v_exp_f32_e32 v159, v175
	v_add_f32_e32 v252, v144, v145
	v_add_f32_e32 v253, v146, v147
	v_add_f32_e32 v254, v148, v149
	v_add_f32_e32 v255, v150, v151
	v_add_f32_e32 v252, v252, v152
	v_add_f32_e32 v253, v253, v153
	v_add_f32_e32 v254, v254, v154
	v_add_f32_e32 v255, v255, v155
	v_add_f32_e32 v252, v252, v156
	v_add_f32_e32 v253, v253, v157
	v_add_f32_e32 v254, v254, v158
	v_add_f32_e32 v255, v255, v159
	v_cvt_pk_bf16_f32 v212, v144, v145
	v_cvt_pk_bf16_f32 v213, v146, v147
	v_add_f32_e32 v252, v252, v253
	v_add_f32_e32 v254, v254, v255
	v_cvt_pk_bf16_f32 v214, v148, v149
	v_cvt_pk_bf16_f32 v215, v150, v151
	v_cvt_pk_bf16_f32 v220, v152, v153
	v_add_f32_e32 v252, v252, v254
	v_cvt_pk_bf16_f32 v221, v154, v155
	v_cvt_pk_bf16_f32 v222, v156, v157
	v_cvt_pk_bf16_f32 v223, v158, v159
	v_add_u32_e32 v253, 0xde801b54, v252
	v_cmp_gt_u32_e32 vcc, 0x3bff7543, v253
	s_cmp_lg_u64 vcc, exec
	s_cbranch_scc1 .Lfzsb1_c0
	v_add_f32_e32 v14, v14, v252
.LBB0_413:
	v_add_u32_e32 v242, s27, v234
	s_cmp_gt_u32 s87, 29
	s_cselect_b64 vcc, -1, 0
	ds_read_b64_tr_b16 v[160:161], v242 offset:0x0
	ds_read_b64_tr_b16 v[162:163], v242 offset:0x100
	ds_read_b64_tr_b16 v[164:165], v242 offset:0x1000
	ds_read_b64_tr_b16 v[166:167], v242 offset:0x1100
	s_waitcnt lgkmcnt(2)
	v_mfma_f32_32x32x16_bf16 v[128:143], v[216:219], v[160:163], v[128:143]
	ds_read_b64_tr_b16 v[168:169], v242 offset:0x200
	v_mfma_f32_32x32x16_bf16 v[96:111], v[212:215], v[160:163], v[96:111]
	ds_read_b64_tr_b16 v[170:171], v242 offset:0x300
	s_cbranch_vccnz .Lnst0_c0
	s_add_i32 s3, s86, 0x8000
	s_and_b32 s3, s3, 0xc000
	s_add_u32 s0, s84, s56
	s_addc_u32 s1, s85, s57
	s_add_u32 s10, s0, s40
	s_addc_u32 s11, s1, s41
	s_add_u32 s0, s0, s18
	s_addc_u32 s1, s1, s19
	s_add_i32 m0, s81, s3
	s_nop 0
	global_load_lds_dwordx4 v250, s[0:1]
.Lnst0_c0:
	s_waitcnt lgkmcnt(2)
	v_mfma_f32_32x32x16_bf16 v[128:143], v[224:227], v[164:167], v[128:143]
	ds_read_b64_tr_b16 v[172:173], v242 offset:0x1200
	v_mfma_f32_32x32x16_bf16 v[96:111], v[220:223], v[164:167], v[96:111]
	ds_read_b64_tr_b16 v[174:175], v242 offset:0x1300
	s_cbranch_vccnz .Lnst1_c0
	s_add_i32 m0, s80, s3
	s_add_i32 s3, s3, 0x2000
	global_load_lds_dwordx4 v251, s[10:11]
.Lnst1_c0:
	s_waitcnt lgkmcnt(2)
	v_mfma_f32_32x32x16_bf16 v[112:127], v[216:219], v[168:171], v[112:127]
	ds_read_b64_tr_b16 v[160:161], v242 offset:0x400
	v_mfma_f32_32x32x16_bf16 v[80:95], v[212:215], v[168:171], v[80:95]
	ds_read_b64_tr_b16 v[162:163], v242 offset:0x500
	s_cbranch_vccnz .Lnst2_c0
	s_add_u32 s0, s0, 0xb8000
	s_addc_u32 s1, s1, 0
	s_add_i32 m0, s81, s3
	s_add_u32 s10, s10, 0xb8000
	s_addc_u32 s11, s11, 0
	global_load_lds_dwordx4 v250, s[0:1]
.Lnst2_c0:
	s_waitcnt lgkmcnt(2)
	v_mfma_f32_32x32x16_bf16 v[112:127], v[224:227], v[172:175], v[112:127]
	ds_read_b64_tr_b16 v[164:165], v242 offset:0x1400
	v_mfma_f32_32x32x16_bf16 v[80:95], v[220:223], v[172:175], v[80:95]
	ds_read_b64_tr_b16 v[166:167], v242 offset:0x1500
	s_cbranch_vccnz .Lnst3_c0
	s_add_i32 m0, s80, s3
	s_nop 0
	global_load_lds_dwordx4 v251, s[10:11]
.Lnst3_c0:
	ds_read_b128 v[144:147], v241 offset:0x2000
	ds_read_b128 v[148:151], v240 offset:0x2000
	ds_read_b128 v[152:155], v239 offset:0x2000
	ds_read_b128 v[156:159], v0 offset:0x2000
	s_waitcnt lgkmcnt(6)
	v_mfma_f32_32x32x16_bf16 v[64:79], v[216:219], v[160:163], v[64:79]
	ds_read_b64_tr_b16 v[168:169], v242 offset:0x600
	v_mfma_f32_32x32x16_bf16 v[32:47], v[212:215], v[160:163], v[32:47]
	ds_read_b64_tr_b16 v[170:171], v242 offset:0x700
	s_waitcnt lgkmcnt(6)
	v_mfma_f32_32x32x16_bf16 v[64:79], v[224:227], v[164:167], v[64:79]
	ds_read_b64_tr_b16 v[172:173], v242 offset:0x1600
	v_mfma_f32_32x32x16_bf16 v[32:47], v[220:223], v[164:167], v[32:47]
	ds_read_b64_tr_b16 v[174:175], v242 offset:0x1700
	s_waitcnt lgkmcnt(2)
	v_mfma_f32_32x32x16_bf16 v[48:63], v[216:219], v[168:171], v[48:63]
	v_mfma_f32_32x32x16_bf16 v[16:31], v[212:215], v[168:171], v[16:31]
	s_waitcnt lgkmcnt(0)
	v_mfma_f32_32x32x16_bf16 v[48:63], v[224:227], v[172:175], v[48:63]
	v_mfma_f32_32x32x16_bf16 v[16:31], v[220:223], v[172:175], v[16:31]
	s_waitcnt lgkmcnt(0)
	v_mfma_f32_32x32x16_bf16 v[212:227], v[144:147], v[176:179], 0
	v_mfma_f32_32x32x16_bf16 v[212:227], v[148:151], v[180:183], v[212:227]
	v_mfma_f32_32x32x16_bf16 v[212:227], v[152:155], v[184:187], v[212:227]
	v_mfma_f32_32x32x16_bf16 v[212:227], v[156:159], v[188:191], v[212:227]
	ds_read_b128 v[144:147], v241 offset:0x2080
	ds_read_b128 v[148:151], v240 offset:0x2080
	ds_read_b128 v[152:155], v239 offset:0x2080
	ds_read_b128 v[156:159], v0 offset:0x2080
	v_cmp_eq_f32_e32 vcc, 0, v238
	v_cmp_eq_f32_e64 s[10:11], 0, v237
	s_and_b64 s[0:1], vcc, s[10:11]
	s_cmp_eq_u64 s[0:1], exec
	s_waitcnt lgkmcnt(0)
	v_mfma_f32_32x32x16_bf16 v[160:175], v[144:147], v[192:195], 0
	v_mfma_f32_32x32x16_bf16 v[160:175], v[148:151], v[196:199], v[160:175]
	v_mfma_f32_32x32x16_bf16 v[160:175], v[152:155], v[200:203], v[160:175]
	v_mfma_f32_32x32x16_bf16 v[160:175], v[156:159], v[204:207], v[160:175]
	s_cbranch_scc0 .Lfz2o_c0
	v_exp_f32_e32 v144, v212
	v_exp_f32_e32 v145, v213
	v_exp_f32_e32 v146, v214
	v_exp_f32_e32 v147, v215
	v_exp_f32_e32 v148, v216
	v_exp_f32_e32 v149, v217
	v_exp_f32_e32 v150, v218
	v_exp_f32_e32 v151, v219
	v_exp_f32_e32 v152, v220
	v_exp_f32_e32 v153, v221
	v_exp_f32_e32 v154, v222
	v_exp_f32_e32 v155, v223
	v_exp_f32_e32 v156, v224
	v_exp_f32_e32 v157, v225
	v_exp_f32_e32 v158, v226
	v_exp_f32_e32 v159, v227
	v_add_f32_e32 v252, v144, v145
	v_add_f32_e32 v253, v146, v147
	v_add_f32_e32 v254, v148, v149
	v_add_f32_e32 v255, v150, v151
	v_add_f32_e32 v252, v252, v152
	v_add_f32_e32 v253, v253, v153
	v_add_f32_e32 v254, v254, v154
	v_add_f32_e32 v255, v255, v155
	v_add_f32_e32 v252, v252, v156
	v_add_f32_e32 v253, v253, v157
	v_add_f32_e32 v254, v254, v158
	v_add_f32_e32 v255, v255, v159
	v_cvt_pk_bf16_f32 v6, v144, v145
	v_cvt_pk_bf16_f32 v7, v146, v147
	v_add_f32_e32 v252, v252, v253
	v_add_f32_e32 v254, v254, v255
	v_cvt_pk_bf16_f32 v8, v148, v149
	v_cvt_pk_bf16_f32 v9, v150, v151
	v_cvt_pk_bf16_f32 v208, v152, v153
	v_add_f32_e32 v252, v252, v254
	v_cvt_pk_bf16_f32 v209, v154, v155
	v_cvt_pk_bf16_f32 v210, v156, v157
	v_cvt_pk_bf16_f32 v211, v158, v159
	v_add_u32_e32 v253, 0xde801b54, v252
	v_cmp_gt_u32_e32 vcc, 0x3bff7543, v253
	s_cmp_lg_u64 vcc, exec
	s_cbranch_scc1 .LBB0_444
	v_add_f32_e32 v15, v15, v252
	v_exp_f32_e32 v144, v160
	v_exp_f32_e32 v145, v161
	v_exp_f32_e32 v146, v162
	v_exp_f32_e32 v147, v163
	v_exp_f32_e32 v148, v164
	v_exp_f32_e32 v149, v165
	v_exp_f32_e32 v150, v166
	v_exp_f32_e32 v151, v167
	v_exp_f32_e32 v152, v168
	v_exp_f32_e32 v153, v169
	v_exp_f32_e32 v154, v170
	v_exp_f32_e32 v155, v171
	v_exp_f32_e32 v156, v172
	v_exp_f32_e32 v157, v173
	v_exp_f32_e32 v158, v174
	v_exp_f32_e32 v159, v175
	v_add_f32_e32 v252, v144, v145
	v_add_f32_e32 v253, v146, v147
	v_add_f32_e32 v254, v148, v149
	v_add_f32_e32 v255, v150, v151
	v_add_f32_e32 v252, v252, v152
	v_add_f32_e32 v253, v253, v153
	v_add_f32_e32 v254, v254, v154
	v_add_f32_e32 v255, v255, v155
	v_add_f32_e32 v252, v252, v156
	v_add_f32_e32 v253, v253, v157
	v_add_f32_e32 v254, v254, v158
	v_add_f32_e32 v255, v255, v159
	v_cvt_pk_bf16_f32 v2, v144, v145
	v_cvt_pk_bf16_f32 v3, v146, v147
	v_add_f32_e32 v252, v252, v253
	v_add_f32_e32 v254, v254, v255
	v_cvt_pk_bf16_f32 v4, v148, v149
	v_cvt_pk_bf16_f32 v5, v150, v151
	v_cvt_pk_bf16_f32 v10, v152, v153
	v_add_f32_e32 v252, v252, v254
	v_cvt_pk_bf16_f32 v11, v154, v155
	v_cvt_pk_bf16_f32 v12, v156, v157
	v_cvt_pk_bf16_f32 v13, v158, v159
	v_add_u32_e32 v253, 0xde801b54, v252
	v_cmp_gt_u32_e32 vcc, 0x3bff7543, v253
	s_cmp_lg_u64 vcc, exec
	s_cbranch_scc1 .Lfzsb2_c0
	v_add_f32_e32 v14, v14, v252

.Lbar_c1:
	s_barrier
.LBB0_1249:
.Lfz1_c1:
	s_and_b32 s27, s77, 0xc000
	v_add_u32_e32 v241, s27, v233
	ds_read_b128 v[144:147], v241 offset:0
	v_xor_b32_e32 v240, 32, v241
	ds_read_b128 v[148:151], v240 offset:0
	v_xor_b32_e32 v239, 64, v241
	ds_read_b128 v[152:155], v239 offset:0
	v_xor_b32_e32 v0, 0x60, v241
	ds_read_b128 v[156:159], v0 offset:0
	s_waitcnt lgkmcnt(0)
	v_mfma_f32_32x32x16_bf16 v[212:227], v[144:147], v[176:179], 0
	v_mfma_f32_32x32x16_bf16 v[212:227], v[148:151], v[180:183], v[212:227]
	v_mfma_f32_32x32x16_bf16 v[212:227], v[152:155], v[184:187], v[212:227]
	v_mfma_f32_32x32x16_bf16 v[212:227], v[156:159], v[188:191], v[212:227]
	ds_read_b128 v[144:147], v241 offset:0x80
	ds_read_b128 v[148:151], v240 offset:0x80
	ds_read_b128 v[152:155], v239 offset:0x80
	ds_read_b128 v[156:159], v0 offset:0x80
	v_cmp_eq_f32_e32 vcc, 0, v238
	v_cmp_eq_f32_e64 s[10:11], 0, v237
	s_and_b64 s[0:1], vcc, s[10:11]
	s_cmp_eq_u64 s[0:1], exec
	s_waitcnt lgkmcnt(0)
	v_mfma_f32_32x32x16_bf16 v[160:175], v[144:147], v[192:195], 0
	v_mfma_f32_32x32x16_bf16 v[160:175], v[148:151], v[196:199], v[160:175]
	v_mfma_f32_32x32x16_bf16 v[160:175], v[152:155], v[200:203], v[160:175]
	v_mfma_f32_32x32x16_bf16 v[160:175], v[156:159], v[204:207], v[160:175]
	s_cbranch_scc0 .LBB0_1251
	v_exp_f32_e32 v144, v212
	v_exp_f32_e32 v145, v213
	v_exp_f32_e32 v146, v214
	v_exp_f32_e32 v147, v215
	v_exp_f32_e32 v148, v216
	v_exp_f32_e32 v149, v217
	v_exp_f32_e32 v150, v218
	v_exp_f32_e32 v151, v219
	v_exp_f32_e32 v152, v220
	v_exp_f32_e32 v153, v221
	v_exp_f32_e32 v154, v222
	v_exp_f32_e32 v155, v223
	v_exp_f32_e32 v156, v224
	v_exp_f32_e32 v157, v225
	v_exp_f32_e32 v158, v226
	v_exp_f32_e32 v159, v227
	v_add_f32_e32 v252, v144, v145
	v_add_f32_e32 v253, v146, v147
	v_add_f32_e32 v254, v148, v149
	v_add_f32_e32 v255, v150, v151
	v_add_f32_e32 v252, v252, v152
	v_add_f32_e32 v253, v253, v153
	v_add_f32_e32 v254, v254, v154
	v_add_f32_e32 v255, v255, v155
	v_add_f32_e32 v252, v252, v156
	v_add_f32_e32 v253, v253, v157
	v_add_f32_e32 v254, v254, v158
	v_add_f32_e32 v255, v255, v159
	v_cvt_pk_bf16_f32 v216, v144, v145
	v_cvt_pk_bf16_f32 v217, v146, v147
	v_add_f32_e32 v252, v252, v253
	v_add_f32_e32 v254, v254, v255
	v_cvt_pk_bf16_f32 v218, v148, v149
	v_cvt_pk_bf16_f32 v219, v150, v151
	v_cvt_pk_bf16_f32 v224, v152, v153
	v_add_f32_e32 v252, v252, v254
	v_cvt_pk_bf16_f32 v225, v154, v155
	v_cvt_pk_bf16_f32 v226, v156, v157
	v_cvt_pk_bf16_f32 v227, v158, v159
	v_add_u32_e32 v253, 0xde801b54, v252
	v_cmp_gt_u32_e32 vcc, 0x3bff7543, v253
	s_cmp_lg_u64 vcc, exec
	s_cbranch_scc1 .LBB0_1286
	v_add_f32_e32 v15, v15, v252
	v_exp_f32_e32 v144, v160
	v_exp_f32_e32 v145, v161
	v_exp_f32_e32 v146, v162
	v_exp_f32_e32 v147, v163
	v_exp_f32_e32 v148, v164
	v_exp_f32_e32 v149, v165
	v_exp_f32_e32 v150, v166
	v_exp_f32_e32 v151, v167
	v_exp_f32_e32 v152, v168
	v_exp_f32_e32 v153, v169
	v_exp_f32_e32 v154, v170
	v_exp_f32_e32 v155, v171
	v_exp_f32_e32 v156, v172
	v_exp_f32_e32 v157, v173
	v_exp_f32_e32 v158, v174
	v_exp_f32_e32 v159, v175
	v_add_f32_e32 v252, v144, v145
	v_add_f32_e32 v253, v146, v147
	v_add_f32_e32 v254, v148, v149
	v_add_f32_e32 v255, v150, v151
	v_add_f32_e32 v252, v252, v152
	v_add_f32_e32 v253, v253, v153
	v_add_f32_e32 v254, v254, v154
	v_add_f32_e32 v255, v255, v155
	v_add_f32_e32 v252, v252, v156
	v_add_f32_e32 v253, v253, v157
	v_add_f32_e32 v254, v254, v158
	v_add_f32_e32 v255, v255, v159
	v_cvt_pk_bf16_f32 v212, v144, v145
	v_cvt_pk_bf16_f32 v213, v146, v147
	v_add_f32_e32 v252, v252, v253
	v_add_f32_e32 v254, v254, v255
	v_cvt_pk_bf16_f32 v214, v148, v149
	v_cvt_pk_bf16_f32 v215, v150, v151
	v_cvt_pk_bf16_f32 v220, v152, v153
	v_add_f32_e32 v252, v252, v254
	v_cvt_pk_bf16_f32 v221, v154, v155
	v_cvt_pk_bf16_f32 v222, v156, v157
	v_cvt_pk_bf16_f32 v223, v158, v159
	v_add_u32_e32 v253, 0xde801b54, v252
	v_cmp_gt_u32_e32 vcc, 0x3bff7543, v253
	s_cmp_lg_u64 vcc, exec
	s_cbranch_scc1 .Lfzsb1_c1
	v_add_f32_e32 v14, v14, v252
.LBB0_1267:
	v_add_u32_e32 v242, s27, v234
	s_cmpk_gt_u32 s79, 0xfd
	s_cselect_b64 vcc, -1, 0
	ds_read_b64_tr_b16 v[160:161], v242 offset:0x0
	ds_read_b64_tr_b16 v[162:163], v242 offset:0x100
	ds_read_b64_tr_b16 v[164:165], v242 offset:0x1000
	ds_read_b64_tr_b16 v[166:167], v242 offset:0x1100
	s_waitcnt lgkmcnt(2)
	v_mfma_f32_32x32x16_bf16 v[128:143], v[216:219], v[160:163], v[128:143]
	ds_read_b64_tr_b16 v[168:169], v242 offset:0x200
	v_mfma_f32_32x32x16_bf16 v[96:111], v[212:215], v[160:163], v[96:111]
	ds_read_b64_tr_b16 v[170:171], v242 offset:0x300
	s_cbranch_vccnz .Lnst0_c1
	s_add_i32 s3, s77, 0x8000
	s_and_b32 s3, s3, 0xc000
	s_add_u32 s0, s69, s86
	s_addc_u32 s1, s76, s87
	s_add_u32 s10, s0, s36
	s_addc_u32 s11, s1, s37
	s_add_u32 s0, s0, s16
	s_addc_u32 s1, s1, s17
	s_add_i32 m0, s68, s3
	s_nop 0
	global_load_lds_dwordx4 v250, s[0:1]
.Lnst0_c1:
	s_waitcnt lgkmcnt(2)
	v_mfma_f32_32x32x16_bf16 v[128:143], v[224:227], v[164:167], v[128:143]
	ds_read_b64_tr_b16 v[172:173], v242 offset:0x1200
	v_mfma_f32_32x32x16_bf16 v[96:111], v[220:223], v[164:167], v[96:111]
	ds_read_b64_tr_b16 v[174:175], v242 offset:0x1300
	s_cbranch_vccnz .Lnst1_c1
	s_add_i32 m0, s57, s3
	s_add_i32 s3, s3, 0x2000
	global_load_lds_dwordx4 v251, s[10:11]
.Lnst1_c1:
	s_waitcnt lgkmcnt(2)
	v_mfma_f32_32x32x16_bf16 v[112:127], v[216:219], v[168:171], v[112:127]
	ds_read_b64_tr_b16 v[160:161], v242 offset:0x400
	v_mfma_f32_32x32x16_bf16 v[80:95], v[212:215], v[168:171], v[80:95]
	ds_read_b64_tr_b16 v[162:163], v242 offset:0x500
	s_cbranch_vccnz .Lnst2_c1
	s_add_u32 s0, s0, 0xb8000
	s_addc_u32 s1, s1, 0
	s_add_i32 m0, s68, s3
	s_add_u32 s10, s10, 0xb8000
	s_addc_u32 s11, s11, 0
	global_load_lds_dwordx4 v250, s[0:1]
.Lnst2_c1:
	s_waitcnt lgkmcnt(2)
	v_mfma_f32_32x32x16_bf16 v[112:127], v[224:227], v[172:175], v[112:127]
	ds_read_b64_tr_b16 v[164:165], v242 offset:0x1400
	v_mfma_f32_32x32x16_bf16 v[80:95], v[220:223], v[172:175], v[80:95]
	ds_read_b64_tr_b16 v[166:167], v242 offset:0x1500
	s_cbranch_vccnz .Lnst3_c1
	s_add_i32 m0, s57, s3
	s_nop 0
	global_load_lds_dwordx4 v251, s[10:11]
.Lnst3_c1:
	ds_read_b128 v[144:147], v241 offset:0x2000
	ds_read_b128 v[148:151], v240 offset:0x2000
	ds_read_b128 v[152:155], v239 offset:0x2000
	ds_read_b128 v[156:159], v0 offset:0x2000
	s_waitcnt lgkmcnt(6)
	v_mfma_f32_32x32x16_bf16 v[64:79], v[216:219], v[160:163], v[64:79]
	ds_read_b64_tr_b16 v[168:169], v242 offset:0x600
	v_mfma_f32_32x32x16_bf16 v[48:63], v[212:215], v[160:163], v[48:63]
	ds_read_b64_tr_b16 v[170:171], v242 offset:0x700
	s_waitcnt lgkmcnt(6)
	v_mfma_f32_32x32x16_bf16 v[64:79], v[224:227], v[164:167], v[64:79]
	ds_read_b64_tr_b16 v[172:173], v242 offset:0x1600
	v_mfma_f32_32x32x16_bf16 v[48:63], v[220:223], v[164:167], v[48:63]
	ds_read_b64_tr_b16 v[174:175], v242 offset:0x1700
	s_waitcnt lgkmcnt(2)
	v_mfma_f32_32x32x16_bf16 v[32:47], v[216:219], v[168:171], v[32:47]
	v_mfma_f32_32x32x16_bf16 v[16:31], v[212:215], v[168:171], v[16:31]
	s_waitcnt lgkmcnt(0)
	v_mfma_f32_32x32x16_bf16 v[32:47], v[224:227], v[172:175], v[32:47]
	v_mfma_f32_32x32x16_bf16 v[16:31], v[220:223], v[172:175], v[16:31]
	s_waitcnt lgkmcnt(0)
	v_mfma_f32_32x32x16_bf16 v[212:227], v[144:147], v[176:179], 0
	v_mfma_f32_32x32x16_bf16 v[212:227], v[148:151], v[180:183], v[212:227]
	v_mfma_f32_32x32x16_bf16 v[212:227], v[152:155], v[184:187], v[212:227]
	v_mfma_f32_32x32x16_bf16 v[212:227], v[156:159], v[188:191], v[212:227]
	ds_read_b128 v[144:147], v241 offset:0x2080
	ds_read_b128 v[148:151], v240 offset:0x2080
	ds_read_b128 v[152:155], v239 offset:0x2080
	ds_read_b128 v[156:159], v0 offset:0x2080
	v_cmp_eq_f32_e32 vcc, 0, v238
	v_cmp_eq_f32_e64 s[10:11], 0, v237
	s_and_b64 s[0:1], vcc, s[10:11]
	s_cmp_eq_u64 s[0:1], exec
	s_waitcnt lgkmcnt(0)
	v_mfma_f32_32x32x16_bf16 v[160:175], v[144:147], v[192:195], 0
	v_mfma_f32_32x32x16_bf16 v[160:175], v[148:151], v[196:199], v[160:175]
	v_mfma_f32_32x32x16_bf16 v[160:175], v[152:155], v[200:203], v[160:175]
	v_mfma_f32_32x32x16_bf16 v[160:175], v[156:159], v[204:207], v[160:175]
	s_cbranch_scc0 .Lfz2o_c1
	v_exp_f32_e32 v144, v212
	v_exp_f32_e32 v145, v213
	v_exp_f32_e32 v146, v214
	v_exp_f32_e32 v147, v215
	v_exp_f32_e32 v148, v216
	v_exp_f32_e32 v149, v217
	v_exp_f32_e32 v150, v218
	v_exp_f32_e32 v151, v219
	v_exp_f32_e32 v152, v220
	v_exp_f32_e32 v153, v221
	v_exp_f32_e32 v154, v222
	v_exp_f32_e32 v155, v223
	v_exp_f32_e32 v156, v224
	v_exp_f32_e32 v157, v225
	v_exp_f32_e32 v158, v226
	v_exp_f32_e32 v159, v227
	v_add_f32_e32 v252, v144, v145
	v_add_f32_e32 v253, v146, v147
	v_add_f32_e32 v254, v148, v149
	v_add_f32_e32 v255, v150, v151
	v_add_f32_e32 v252, v252, v152
	v_add_f32_e32 v253, v253, v153
	v_add_f32_e32 v254, v254, v154
	v_add_f32_e32 v255, v255, v155
	v_add_f32_e32 v252, v252, v156
	v_add_f32_e32 v253, v253, v157
	v_add_f32_e32 v254, v254, v158
	v_add_f32_e32 v255, v255, v159
	v_cvt_pk_bf16_f32 v6, v144, v145
	v_cvt_pk_bf16_f32 v7, v146, v147
	v_add_f32_e32 v252, v252, v253
	v_add_f32_e32 v254, v254, v255
	v_cvt_pk_bf16_f32 v8, v148, v149
	v_cvt_pk_bf16_f32 v9, v150, v151
	v_cvt_pk_bf16_f32 v208, v152, v153
	v_add_f32_e32 v252, v252, v254
	v_cvt_pk_bf16_f32 v209, v154, v155
	v_cvt_pk_bf16_f32 v210, v156, v157
	v_cvt_pk_bf16_f32 v211, v158, v159
	v_add_u32_e32 v253, 0xde801b54, v252
	v_cmp_gt_u32_e32 vcc, 0x3bff7543, v253
	s_cmp_lg_u64 vcc, exec
	s_cbranch_scc1 .LBB0_1298
	v_add_f32_e32 v15, v15, v252
	v_exp_f32_e32 v144, v160
	v_exp_f32_e32 v145, v161
	v_exp_f32_e32 v146, v162
	v_exp_f32_e32 v147, v163
	v_exp_f32_e32 v148, v164
	v_exp_f32_e32 v149, v165
	v_exp_f32_e32 v150, v166
	v_exp_f32_e32 v151, v167
	v_exp_f32_e32 v152, v168
	v_exp_f32_e32 v153, v169
	v_exp_f32_e32 v154, v170
	v_exp_f32_e32 v155, v171
	v_exp_f32_e32 v156, v172
	v_exp_f32_e32 v157, v173
	v_exp_f32_e32 v158, v174
	v_exp_f32_e32 v159, v175
	v_add_f32_e32 v252, v144, v145
	v_add_f32_e32 v253, v146, v147
	v_add_f32_e32 v254, v148, v149
	v_add_f32_e32 v255, v150, v151
	v_add_f32_e32 v252, v252, v152
	v_add_f32_e32 v253, v253, v153
	v_add_f32_e32 v254, v254, v154
	v_add_f32_e32 v255, v255, v155
	v_add_f32_e32 v252, v252, v156
	v_add_f32_e32 v253, v253, v157
	v_add_f32_e32 v254, v254, v158
	v_add_f32_e32 v255, v255, v159
	v_cvt_pk_bf16_f32 v2, v144, v145
	v_cvt_pk_bf16_f32 v3, v146, v147
	v_add_f32_e32 v252, v252, v253
	v_add_f32_e32 v254, v254, v255
	v_cvt_pk_bf16_f32 v4, v148, v149
	v_cvt_pk_bf16_f32 v5, v150, v151
	v_cvt_pk_bf16_f32 v10, v152, v153
	v_add_f32_e32 v252, v252, v254
	v_cvt_pk_bf16_f32 v11, v154, v155
	v_cvt_pk_bf16_f32 v12, v156, v157
	v_cvt_pk_bf16_f32 v13, v158, v159
	v_add_u32_e32 v253, 0xde801b54, v252
	v_cmp_gt_u32_e32 vcc, 0x3bff7543, v253
	s_cmp_lg_u64 vcc, exec
	s_cbranch_scc1 .Lfzsb2_c1
	v_add_f32_e32 v14, v14, v252

.Lbar_c2:
	s_barrier
.LBB0_2103:
.Lfz1_c2:
	s_and_b32 s27, s68, 0xc000
	v_add_u32_e32 v241, s27, v233
	ds_read_b128 v[144:147], v241 offset:0
	v_xor_b32_e32 v240, 32, v241
	ds_read_b128 v[148:151], v240 offset:0
	v_xor_b32_e32 v239, 64, v241
	ds_read_b128 v[152:155], v239 offset:0
	v_xor_b32_e32 v0, 0x60, v241
	ds_read_b128 v[156:159], v0 offset:0
	s_waitcnt lgkmcnt(0)
	v_mfma_f32_32x32x16_bf16 v[212:227], v[144:147], v[176:179], 0
	v_mfma_f32_32x32x16_bf16 v[212:227], v[148:151], v[180:183], v[212:227]
	v_mfma_f32_32x32x16_bf16 v[212:227], v[152:155], v[184:187], v[212:227]
	v_mfma_f32_32x32x16_bf16 v[212:227], v[156:159], v[188:191], v[212:227]
	ds_read_b128 v[144:147], v241 offset:0x80
	ds_read_b128 v[148:151], v240 offset:0x80
	ds_read_b128 v[152:155], v239 offset:0x80
	ds_read_b128 v[156:159], v0 offset:0x80
	v_cmp_eq_f32_e32 vcc, 0, v238
	v_cmp_eq_f32_e64 s[6:7], 0, v237
	s_and_b64 s[0:1], vcc, s[6:7]
	s_cmp_eq_u64 s[0:1], exec
	s_waitcnt lgkmcnt(0)
	v_mfma_f32_32x32x16_bf16 v[160:175], v[144:147], v[192:195], 0
	v_mfma_f32_32x32x16_bf16 v[160:175], v[148:151], v[196:199], v[160:175]
	v_mfma_f32_32x32x16_bf16 v[160:175], v[152:155], v[200:203], v[160:175]
	v_mfma_f32_32x32x16_bf16 v[160:175], v[156:159], v[204:207], v[160:175]
	s_cbranch_scc0 .LBB0_2105
	v_exp_f32_e32 v144, v212
	v_exp_f32_e32 v145, v213
	v_exp_f32_e32 v146, v214
	v_exp_f32_e32 v147, v215
	v_exp_f32_e32 v148, v216
	v_exp_f32_e32 v149, v217
	v_exp_f32_e32 v150, v218
	v_exp_f32_e32 v151, v219
	v_exp_f32_e32 v152, v220
	v_exp_f32_e32 v153, v221
	v_exp_f32_e32 v154, v222
	v_exp_f32_e32 v155, v223
	v_exp_f32_e32 v156, v224
	v_exp_f32_e32 v157, v225
	v_exp_f32_e32 v158, v226
	v_exp_f32_e32 v159, v227
	v_add_f32_e32 v252, v144, v145
	v_add_f32_e32 v253, v146, v147
	v_add_f32_e32 v254, v148, v149
	v_add_f32_e32 v255, v150, v151
	v_add_f32_e32 v252, v252, v152
	v_add_f32_e32 v253, v253, v153
	v_add_f32_e32 v254, v254, v154
	v_add_f32_e32 v255, v255, v155
	v_add_f32_e32 v252, v252, v156
	v_add_f32_e32 v253, v253, v157
	v_add_f32_e32 v254, v254, v158
	v_add_f32_e32 v255, v255, v159
	v_cvt_pk_bf16_f32 v216, v144, v145
	v_cvt_pk_bf16_f32 v217, v146, v147
	v_add_f32_e32 v252, v252, v253
	v_add_f32_e32 v254, v254, v255
	v_cvt_pk_bf16_f32 v218, v148, v149
	v_cvt_pk_bf16_f32 v219, v150, v151
	v_cvt_pk_bf16_f32 v224, v152, v153
	v_add_f32_e32 v252, v252, v254
	v_cvt_pk_bf16_f32 v225, v154, v155
	v_cvt_pk_bf16_f32 v226, v156, v157
	v_cvt_pk_bf16_f32 v227, v158, v159
	v_add_u32_e32 v253, 0xde801b54, v252
	v_cmp_gt_u32_e32 vcc, 0x3bff7543, v253
	s_cmp_lg_u64 vcc, exec
	s_cbranch_scc1 .LBB0_2140
	v_add_f32_e32 v15, v15, v252
	v_exp_f32_e32 v144, v160
	v_exp_f32_e32 v145, v161
	v_exp_f32_e32 v146, v162
	v_exp_f32_e32 v147, v163
	v_exp_f32_e32 v148, v164
	v_exp_f32_e32 v149, v165
	v_exp_f32_e32 v150, v166
	v_exp_f32_e32 v151, v167
	v_exp_f32_e32 v152, v168
	v_exp_f32_e32 v153, v169
	v_exp_f32_e32 v154, v170
	v_exp_f32_e32 v155, v171
	v_exp_f32_e32 v156, v172
	v_exp_f32_e32 v157, v173
	v_exp_f32_e32 v158, v174
	v_exp_f32_e32 v159, v175
	v_add_f32_e32 v252, v144, v145
	v_add_f32_e32 v253, v146, v147
	v_add_f32_e32 v254, v148, v149
	v_add_f32_e32 v255, v150, v151
	v_add_f32_e32 v252, v252, v152
	v_add_f32_e32 v253, v253, v153
	v_add_f32_e32 v254, v254, v154
	v_add_f32_e32 v255, v255, v155
	v_add_f32_e32 v252, v252, v156
	v_add_f32_e32 v253, v253, v157
	v_add_f32_e32 v254, v254, v158
	v_add_f32_e32 v255, v255, v159
	v_cvt_pk_bf16_f32 v212, v144, v145
	v_cvt_pk_bf16_f32 v213, v146, v147
	v_add_f32_e32 v252, v252, v253
	v_add_f32_e32 v254, v254, v255
	v_cvt_pk_bf16_f32 v214, v148, v149
	v_cvt_pk_bf16_f32 v215, v150, v151
	v_cvt_pk_bf16_f32 v220, v152, v153
	v_add_f32_e32 v252, v252, v254
	v_cvt_pk_bf16_f32 v221, v154, v155
	v_cvt_pk_bf16_f32 v222, v156, v157
	v_cvt_pk_bf16_f32 v223, v158, v159
	v_add_u32_e32 v253, 0xde801b54, v252
	v_cmp_gt_u32_e32 vcc, 0x3bff7543, v253
	s_cmp_lg_u64 vcc, exec
	s_cbranch_scc1 .Lfzsb1_c2
	v_add_f32_e32 v14, v14, v252
.LBB0_2121:
	v_add_u32_e32 v242, s27, v234
	s_cmpk_gt_u32 s69, 0xfd
	s_cselect_b64 vcc, -1, 0
	ds_read_b64_tr_b16 v[160:161], v242 offset:0x0
	ds_read_b64_tr_b16 v[162:163], v242 offset:0x100
	ds_read_b64_tr_b16 v[164:165], v242 offset:0x1000
	ds_read_b64_tr_b16 v[166:167], v242 offset:0x1100
	s_waitcnt lgkmcnt(2)
	v_mfma_f32_32x32x16_bf16 v[128:143], v[216:219], v[160:163], v[128:143]
	ds_read_b64_tr_b16 v[168:169], v242 offset:0x200
	v_mfma_f32_32x32x16_bf16 v[96:111], v[212:215], v[160:163], v[96:111]
	ds_read_b64_tr_b16 v[170:171], v242 offset:0x300
	s_cbranch_vccnz .Lnst0_c2
	s_add_i32 s3, s68, 0x8000
	s_and_b32 s3, s3, 0xc000
	s_add_u32 s0, s66, s58
	s_addc_u32 s1, s67, s59
	s_add_u32 s6, s0, s16
	s_addc_u32 s7, s1, s17
	s_add_u32 s0, s0, s14
	s_addc_u32 s1, s1, s15
	s_add_i32 m0, s65, s3
	s_nop 0
	global_load_lds_dwordx4 v250, s[0:1]
.Lnst0_c2:
	s_waitcnt lgkmcnt(2)
	v_mfma_f32_32x32x16_bf16 v[128:143], v[224:227], v[164:167], v[128:143]
	ds_read_b64_tr_b16 v[172:173], v242 offset:0x1200
	v_mfma_f32_32x32x16_bf16 v[96:111], v[220:223], v[164:167], v[96:111]
	ds_read_b64_tr_b16 v[174:175], v242 offset:0x1300
	s_cbranch_vccnz .Lnst1_c2
	s_add_i32 m0, s64, s3
	s_add_i32 s3, s3, 0x2000
	global_load_lds_dwordx4 v251, s[6:7]
.Lnst1_c2:
	s_waitcnt lgkmcnt(2)
	v_mfma_f32_32x32x16_bf16 v[112:127], v[216:219], v[168:171], v[112:127]
	ds_read_b64_tr_b16 v[160:161], v242 offset:0x400
	v_mfma_f32_32x32x16_bf16 v[80:95], v[212:215], v[168:171], v[80:95]
	ds_read_b64_tr_b16 v[162:163], v242 offset:0x500
	s_cbranch_vccnz .Lnst2_c2
	s_add_u32 s0, s0, 0xb8000
	s_addc_u32 s1, s1, 0
	s_add_i32 m0, s65, s3
	s_add_u32 s6, s6, 0xb8000
	s_addc_u32 s7, s7, 0
	global_load_lds_dwordx4 v250, s[0:1]
.Lnst2_c2:
	s_waitcnt lgkmcnt(2)
	v_mfma_f32_32x32x16_bf16 v[112:127], v[224:227], v[172:175], v[112:127]
	ds_read_b64_tr_b16 v[164:165], v242 offset:0x1400
	v_mfma_f32_32x32x16_bf16 v[80:95], v[220:223], v[172:175], v[80:95]
	ds_read_b64_tr_b16 v[166:167], v242 offset:0x1500
	s_cbranch_vccnz .Lnst3_c2
	s_add_i32 m0, s64, s3
	s_nop 0
	global_load_lds_dwordx4 v251, s[6:7]
.Lnst3_c2:
	ds_read_b128 v[144:147], v241 offset:0x2000
	ds_read_b128 v[148:151], v240 offset:0x2000
	ds_read_b128 v[156:159], v239 offset:0x2000
	ds_read_b128 v[244:247], v0 offset:0x2000
	s_waitcnt lgkmcnt(6)
	v_mfma_f32_32x32x16_bf16 v[64:79], v[216:219], v[160:163], v[64:79]
	ds_read_b64_tr_b16 v[168:169], v242 offset:0x600
	v_mfma_f32_32x32x16_bf16 v[32:47], v[212:215], v[160:163], v[32:47]
	ds_read_b64_tr_b16 v[170:171], v242 offset:0x700
	s_waitcnt lgkmcnt(6)
	v_mfma_f32_32x32x16_bf16 v[64:79], v[224:227], v[164:167], v[64:79]
	ds_read_b64_tr_b16 v[172:173], v242 offset:0x1600
	v_mfma_f32_32x32x16_bf16 v[32:47], v[220:223], v[164:167], v[32:47]
	ds_read_b64_tr_b16 v[174:175], v242 offset:0x1700
	s_waitcnt lgkmcnt(2)
	v_mfma_f32_32x32x16_bf16 v[48:63], v[216:219], v[168:171], v[48:63]
	v_mfma_f32_32x32x16_bf16 v[16:31], v[212:215], v[168:171], v[16:31]
	s_waitcnt lgkmcnt(0)
	v_mfma_f32_32x32x16_bf16 v[48:63], v[224:227], v[172:175], v[48:63]
	v_mfma_f32_32x32x16_bf16 v[16:31], v[220:223], v[172:175], v[16:31]
	s_waitcnt lgkmcnt(0)
	v_mfma_f32_32x32x16_bf16 v[212:227], v[144:147], v[176:179], 0
	v_mfma_f32_32x32x16_bf16 v[212:227], v[148:151], v[180:183], v[212:227]
	v_mfma_f32_32x32x16_bf16 v[212:227], v[156:159], v[184:187], v[212:227]
	v_mfma_f32_32x32x16_bf16 v[212:227], v[244:247], v[188:191], v[212:227]
	ds_read_b128 v[144:147], v241 offset:0x2080
	ds_read_b128 v[148:151], v240 offset:0x2080
	ds_read_b128 v[152:155], v239 offset:0x2080
	ds_read_b128 v[156:159], v0 offset:0x2080
	v_cmp_eq_f32_e32 vcc, 0, v238
	v_cmp_eq_f32_e64 s[6:7], 0, v237
	s_and_b64 s[0:1], vcc, s[6:7]
	s_cmp_eq_u64 s[0:1], exec
	s_waitcnt lgkmcnt(0)
	v_mfma_f32_32x32x16_bf16 v[160:175], v[144:147], v[192:195], 0
	v_mfma_f32_32x32x16_bf16 v[160:175], v[148:151], v[196:199], v[160:175]
	v_mfma_f32_32x32x16_bf16 v[160:175], v[152:155], v[200:203], v[160:175]
	v_mfma_f32_32x32x16_bf16 v[160:175], v[156:159], v[204:207], v[160:175]
	s_cbranch_scc0 .Lfz2o_c2
	v_exp_f32_e32 v144, v212
	v_exp_f32_e32 v145, v213
	v_exp_f32_e32 v146, v214
	v_exp_f32_e32 v147, v215
	v_exp_f32_e32 v148, v216
	v_exp_f32_e32 v149, v217
	v_exp_f32_e32 v150, v218
	v_exp_f32_e32 v151, v219
	v_exp_f32_e32 v152, v220
	v_exp_f32_e32 v153, v221
	v_exp_f32_e32 v154, v222
	v_exp_f32_e32 v155, v223
	v_exp_f32_e32 v156, v224
	v_exp_f32_e32 v157, v225
	v_exp_f32_e32 v158, v226
	v_exp_f32_e32 v159, v227
	v_add_f32_e32 v252, v144, v145
	v_add_f32_e32 v253, v146, v147
	v_add_f32_e32 v254, v148, v149
	v_add_f32_e32 v255, v150, v151
	v_add_f32_e32 v252, v252, v152
	v_add_f32_e32 v253, v253, v153
	v_add_f32_e32 v254, v254, v154
	v_add_f32_e32 v255, v255, v155
	v_add_f32_e32 v252, v252, v156
	v_add_f32_e32 v253, v253, v157
	v_add_f32_e32 v254, v254, v158
	v_add_f32_e32 v255, v255, v159
	v_cvt_pk_bf16_f32 v6, v144, v145
	v_cvt_pk_bf16_f32 v7, v146, v147
	v_add_f32_e32 v252, v252, v253
	v_add_f32_e32 v254, v254, v255
	v_cvt_pk_bf16_f32 v8, v148, v149
	v_cvt_pk_bf16_f32 v9, v150, v151
	v_cvt_pk_bf16_f32 v208, v152, v153
	v_add_f32_e32 v252, v252, v254
	v_cvt_pk_bf16_f32 v209, v154, v155
	v_cvt_pk_bf16_f32 v210, v156, v157
	v_cvt_pk_bf16_f32 v211, v158, v159
	v_add_u32_e32 v253, 0xde801b54, v252
	v_cmp_gt_u32_e32 vcc, 0x3bff7543, v253
	s_cmp_lg_u64 vcc, exec
	s_cbranch_scc1 .LBB0_2152
	v_add_f32_e32 v15, v15, v252
	v_exp_f32_e32 v144, v160
	v_exp_f32_e32 v145, v161
	v_exp_f32_e32 v146, v162
	v_exp_f32_e32 v147, v163
	v_exp_f32_e32 v148, v164
	v_exp_f32_e32 v149, v165
	v_exp_f32_e32 v150, v166
	v_exp_f32_e32 v151, v167
	v_exp_f32_e32 v152, v168
	v_exp_f32_e32 v153, v169
	v_exp_f32_e32 v154, v170
	v_exp_f32_e32 v155, v171
	v_exp_f32_e32 v156, v172
	v_exp_f32_e32 v157, v173
	v_exp_f32_e32 v158, v174
	v_exp_f32_e32 v159, v175
	v_add_f32_e32 v252, v144, v145
	v_add_f32_e32 v253, v146, v147
	v_add_f32_e32 v254, v148, v149
	v_add_f32_e32 v255, v150, v151
	v_add_f32_e32 v252, v252, v152
	v_add_f32_e32 v253, v253, v153
	v_add_f32_e32 v254, v254, v154
	v_add_f32_e32 v255, v255, v155
	v_add_f32_e32 v252, v252, v156
	v_add_f32_e32 v253, v253, v157
	v_add_f32_e32 v254, v254, v158
	v_add_f32_e32 v255, v255, v159
	v_cvt_pk_bf16_f32 v2, v144, v145
	v_cvt_pk_bf16_f32 v3, v146, v147
	v_add_f32_e32 v252, v252, v253
	v_add_f32_e32 v254, v254, v255
	v_cvt_pk_bf16_f32 v4, v148, v149
	v_cvt_pk_bf16_f32 v5, v150, v151
	v_cvt_pk_bf16_f32 v10, v152, v153
	v_add_f32_e32 v252, v252, v254
	v_cvt_pk_bf16_f32 v11, v154, v155
	v_cvt_pk_bf16_f32 v12, v156, v157
	v_cvt_pk_bf16_f32 v13, v158, v159
	v_add_u32_e32 v253, 0xde801b54, v252
	v_cmp_gt_u32_e32 vcc, 0x3bff7543, v253
	s_cmp_lg_u64 vcc, exec
	s_cbranch_scc1 .Lfzsb2_c2
	v_add_f32_e32 v14, v14, v252
